# pipelined GLU gate epilogue, G1 prefetch with scalar bases, FF2 row order reversed
# baseline (speedup 1.0000x reference)
.LBB0_368:
	v_mov_b32_e32 v54, v204
	v_mov_b32_e32 v0, s59
	ds_read_b64 v[10:11], v0
	v_mov_b32_e32 v0, s45
	ds_read2_b64 v[26:29], v0 offset1:1
	s_and_b32 s26, s9, 3
	v_and_b32_e32 v32, 63, v54
	v_lshrrev_b32_e32 v55, 3, v54
	v_readfirstlane_b32 s10, v54
	v_and_b32_e32 v34, 0x7f, v54
	v_and_b32_e32 v0, 7, v54
	v_mul_u32_u24_e32 v55, 0x1400, v55
	v_lshl_add_u32 v0, v0, 3, v55
	v_add_u32_e32 v0, 0x1200, v0
	v_lshlrev_b32_e32 v33, 1, v32
	v_lshlrev_b32_e32 v34, 1, v34
	v_lshlrev_b32_e32 v32, 2, v32
	s_lshr_b32 s10, s10, 6
	s_mul_i32 s11, s7, 0x1400
	s_waitcnt lgkmcnt(0)
	v_readfirstlane_b32 s4, v10
	v_readfirstlane_b32 s5, v11
	v_readfirstlane_b32 s22, v26
	v_readfirstlane_b32 s23, v27
	s_add_u32 s4, s4, 0xe000000
	s_addc_u32 s5, s5, 0
	s_add_u32 s4, s4, s11
	s_addc_u32 s5, s5, 0
	global_load_dwordx2 v[10:11], v0, s[4:5]
	s_add_i32 s11, s21, s10
	s_lshl_b32 s11, s11, 10
	s_lshl_b32 s78, s26, 8
	s_add_i32 s11, s11, s78
	s_add_u32 s22, s22, s11
	s_addc_u32 s23, s23, 0
	global_load_dword v40, v32, s[22:23]
	s_add_u32 s22, s22, 0x2000
	s_addc_u32 s23, s23, 0
	global_load_dword v39, v32, s[22:23]
	s_add_u32 s22, s22, 0x2000
	s_addc_u32 s23, s23, 0
	global_load_dword v38, v32, s[22:23]
	s_add_u32 s22, s22, 0x2000
	s_addc_u32 s23, s23, 0
	global_load_dword v37, v32, s[22:23]
	v_readfirstlane_b32 s22, v28
	v_readfirstlane_b32 s23, v29
	s_lshl_b32 s11, s84, 2
	s_add_i32 s11, s11, s78
	s_add_u32 s22, s22, s11
	s_addc_u32 s23, s23, 0
	global_load_dword v41, v32, s[22:23]
	global_load_dword v36, v32, s[22:23] offset:1024
	s_mul_i32 s11, s10, 0xa000
	s_lshl_b32 s22, s26, 7
	s_add_i32 s11, s11, s22
	s_add_u32 s22, s4, s11
	s_addc_u32 s23, s5, 0
	global_load_ushort v49, v33, s[22:23] offset:512
	s_add_u32 s22, s22, 0x1400
	s_addc_u32 s23, s23, 0
	global_load_ushort v48, v33, s[22:23] offset:512
	s_add_u32 s22, s22, 0x1400
	s_addc_u32 s23, s23, 0
	global_load_ushort v47, v33, s[22:23] offset:512
	s_add_u32 s22, s22, 0x1400
	s_addc_u32 s23, s23, 0
	global_load_ushort v46, v33, s[22:23] offset:512
	s_add_u32 s22, s22, 0x1400
	s_addc_u32 s23, s23, 0
	global_load_ushort v45, v33, s[22:23] offset:512
	s_add_u32 s22, s22, 0x1400
	s_addc_u32 s23, s23, 0
	global_load_ushort v44, v33, s[22:23] offset:512
	s_add_u32 s22, s22, 0x1400
	s_addc_u32 s23, s23, 0
	global_load_ushort v43, v33, s[22:23] offset:512
	s_add_u32 s22, s22, 0x1400
	s_addc_u32 s23, s23, 0
	global_load_ushort v42, v33, s[22:23] offset:512
	s_lshr_b32 s10, s10, 1
	s_mul_i32 s11, s10, 0x14000
	s_add_i32 s11, s11, s78
	s_add_u32 s22, s4, s11
	s_addc_u32 s23, s5, 0
	global_load_ushort v50, v34, s[22:23] offset:1024
	s_add_u32 s22, s22, 0x1400
	s_addc_u32 s23, s23, 0
	global_load_ushort v173, v34, s[22:23] offset:1024
	s_add_u32 s22, s22, 0x1400
	s_addc_u32 s23, s23, 0
	global_load_ushort v174, v34, s[22:23] offset:1024
	s_add_u32 s22, s22, 0x1400
	s_addc_u32 s23, s23, 0
	global_load_ushort v175, v34, s[22:23] offset:1024
	s_add_u32 s22, s22, 0x1400
	s_addc_u32 s23, s23, 0
	global_load_ushort v176, v34, s[22:23] offset:1024
	s_add_u32 s22, s22, 0x1400
	s_addc_u32 s23, s23, 0
	global_load_ushort v177, v34, s[22:23] offset:1024
	s_add_u32 s22, s22, 0x1400
	s_addc_u32 s23, s23, 0
	global_load_ushort v178, v34, s[22:23] offset:1024
	s_add_u32 s22, s22, 0x1400
	s_addc_u32 s23, s23, 0
	global_load_ushort v51, v34, s[22:23] offset:1024
	s_add_u32 s22, s22, 0x1400
	s_addc_u32 s23, s23, 0
	global_load_ushort v54, v34, s[22:23] offset:1024
	s_add_u32 s22, s22, 0x1400
	s_addc_u32 s23, s23, 0
	global_load_ushort v58, v34, s[22:23] offset:1024
	s_add_u32 s22, s22, 0x1400
	s_addc_u32 s23, s23, 0
	global_load_ushort v179, v34, s[22:23] offset:1024
	s_add_u32 s22, s22, 0x1400
	s_addc_u32 s23, s23, 0
	global_load_ushort v180, v34, s[22:23] offset:1024
	s_add_u32 s22, s22, 0x1400
	s_addc_u32 s23, s23, 0
	global_load_ushort v181, v34, s[22:23] offset:1024
	s_add_u32 s22, s22, 0x1400
	s_addc_u32 s23, s23, 0
	global_load_ushort v182, v34, s[22:23] offset:1024
	s_add_u32 s22, s22, 0x1400
	s_addc_u32 s23, s23, 0
	global_load_ushort v56, v34, s[22:23] offset:1024
	s_add_u32 s22, s22, 0x1400
	s_addc_u32 s23, s23, 0
	global_load_ushort v52, v34, s[22:23] offset:1024
	s_waitcnt lgkmcnt(0)

.LBB0_671:
	s_sext_i32_i16 s0, s4
	s_lshl_b32 s4, s8, 3
	s_and_b32 s1, s4, 0xfff8
	v_cvt_f32_i32_e32 v0, s1
	s_lshr_b32 s0, s0, 3
	s_add_i32 s6, s0, s6
	s_sext_i32_i16 s0, s6
	v_cvt_f32_i32_e32 v2, s0
	v_rcp_iflag_f32_e32 v3, v0
	s_ashr_i32 s0, s0, 30
	s_or_b32 s7, s0, 1
	v_mul_f32_e32 v3, v2, v3
	v_trunc_f32_e32 v3, v3
	v_fma_f32 v2, -v3, v0, v2
	v_cvt_i32_f32_e32 v3, v3
	v_cmp_ge_f32_e64 s[0:1], |v2|, v0
	s_and_b64 s[0:1], s[0:1], exec
	s_cselect_b32 s0, s7, 0
	v_readfirstlane_b32 s1, v3
	s_add_i32 s0, s1, s0
	s_sext_i32_i16 s1, s0
	s_lshl_b32 s7, s1, 3
	s_sub_i32 s1, s25, s7
	s_min_i32 s11, s1, 8
	s_sext_i32_i16 s1, s11
	v_cvt_f32_i32_e32 v0, s1
	s_mul_i32 s0, s0, s4
	s_sub_i32 s4, s6, s0
	s_sext_i32_i16 s0, s4
	v_cvt_f32_i32_e32 v2, s0
	v_rcp_iflag_f32_e32 v3, v0
	s_xor_b32 s0, s0, s1
	s_ashr_i32 s0, s0, 30
	s_or_b32 s6, s0, 1
	v_mul_f32_e32 v3, v2, v3
	v_trunc_f32_e32 v3, v3
	v_fma_f32 v2, -v3, v0, v2
	v_cvt_i32_f32_e32 v3, v3
	v_cmp_ge_f32_e64 s[0:1], |v2|, |v0|
	s_and_b64 s[0:1], s[0:1], exec
	s_cselect_b32 s0, s6, 0
	v_readfirstlane_b32 s1, v3
	s_add_i32 s0, s1, s0
	s_sext_i32_i16 s91, s0
	s_mul_i32 s0, s0, s11
	s_sub_i32 s0, s4, s0
	s_sext_i32_i16 s0, s0
	s_add_i32 s87, s7, s0
	s_cmp_lg_u32 s26, 4
	s_cbranch_scc1 .LBB0_672
	s_sub_i32 s87, 0x7f, s87

.LBB0_687:
	s_cmp_lg_u32 s26, 4
	s_cbranch_scc1 .Lrev_next_done
	s_sub_i32 s86, 0x7f, s86

.LBB0_712:
	s_and_b64 vcc, exec, s[10:11]
	v_ashrrev_i32_e32 v159, 31, v158
	v_add_u32_e32 v170, 16, v156
	v_add_u32_e32 v168, 32, v156
	v_add_u32_e32 v166, 48, v156
	v_add_u32_e32 v164, 0x80, v156
	v_add_u32_e32 v162, 0x90, v156
	v_add_u32_e32 v160, 0xa0, v156
	s_cbranch_vccz .LBB0_714
	v_mov_b32_e32 v130, s59
	ds_read_b64 v[130:131], v130
	v_readlane_b32 s10, v245, 59
	v_lshlrev_b64 v[184:185], 1, v[158:159]
	v_ashrrev_i32_e32 v157, 31, v156
	v_ashrrev_i32_e32 v171, 31, v170
	s_waitcnt lgkmcnt(0)
	v_readfirstlane_b32 s52, v130
	v_mov_b32_e32 v130, s10
	v_readfirstlane_b32 s53, v131
	ds_read_b64 v[130:131], v130
	v_readlane_b32 s10, v245, 4
	v_readlane_b32 s11, v245, 5
	s_lshl_b64 s[10:11], s[10:11], 2
	v_lshl_add_u64 v[140:141], s[52:53], 0, v[184:185]
	s_waitcnt lgkmcnt(0)
	v_readfirstlane_b32 s34, v130
	v_readfirstlane_b32 s33, v131
	s_add_u32 s10, s34, s10
	s_addc_u32 s11, s33, s11
	v_lshl_add_u64 v[138:139], v[158:159], 2, s[10:11]
	global_load_dwordx4 v[134:137], v[138:139], off
	global_load_dwordx4 v[130:133], v[138:139], off offset:16
	global_load_dwordx4 v[160:163], v[138:139], off offset:512
	global_load_dwordx4 v[164:167], v[138:139], off offset:528
	s_mov_b64 s[10:11], 0xcc00000
	v_lshl_add_u64 v[198:199], v[140:141], 0, s[10:11]
	v_lshlrev_b64 v[140:141], 9, v[156:157]
	v_lshl_add_u64 v[140:141], v[198:199], 0, v[140:141]
	v_lshlrev_b64 v[168:169], 11, v[156:157]
	v_lshl_add_u64 v[168:169], s[52:53], 0, v[168:169]
	v_lshl_add_u64 v[168:169], v[168:169], 0, v[184:185]
	s_mov_b64 s[10:11], 0x8800000
	v_lshl_add_u64 v[168:169], v[168:169], 0, s[10:11]
	global_load_dwordx4 v[226:229], v[140:141], off
	s_mov_b64 s[10:11], 0x2000
	v_lshl_add_u64 v[242:243], v[140:141], 0, s[10:11]
	global_load_dwordx4 v[230:233], v[242:243], off
	s_mov_b64 s[10:11], 0x4000
	v_lshl_add_u64 v[198:199], v[140:141], 0, s[10:11]
	global_load_dwordx4 v[234:237], v[198:199], off
	s_mov_b64 s[10:11], 0x6000
	v_lshl_add_u64 v[242:243], v[140:141], 0, s[10:11]
	global_load_dwordx4 v[238:241], v[242:243], off
	s_mov_b64 s[10:11], 0x10000
	v_lshl_add_u64 v[198:199], v[140:141], 0, s[10:11]
	global_load_dwordx4 v[170:173], v[198:199], off
	s_mov_b64 s[10:11], 0x12000
	v_lshl_add_u64 v[242:243], v[140:141], 0, s[10:11]
	global_load_dwordx4 v[174:177], v[242:243], off
	s_mov_b64 s[10:11], 0x14000
	v_lshl_add_u64 v[198:199], v[140:141], 0, s[10:11]
	global_load_dwordx4 v[178:181], v[198:199], off
	s_mov_b64 s[10:11], 0x16000
	v_lshl_add_u64 v[242:243], v[140:141], 0, s[10:11]
	global_load_dwordx4 v[186:189], v[242:243], off
	s_waitcnt vmcnt(7)
	v_add_f32_e32 v190, v126, v134
	v_add_f32_e32 v191, v127, v135
	v_add_f32_e32 v192, v128, v136
	v_add_f32_e32 v193, v129, v137
	v_add_f32_e32 v194, v122, v130
	v_add_f32_e32 v195, v123, v131
	v_add_f32_e32 v196, v124, v132
	v_add_f32_e32 v197, v125, v133
	v_mul_f32_e32 v190, 0xbfb8aa3b, v190
	v_mul_f32_e32 v191, 0xbfb8aa3b, v191
	v_mul_f32_e32 v192, 0xbfb8aa3b, v192
	v_mul_f32_e32 v193, 0xbfb8aa3b, v193
	v_mul_f32_e32 v194, 0xbfb8aa3b, v194
	v_mul_f32_e32 v195, 0xbfb8aa3b, v195
	v_mul_f32_e32 v196, 0xbfb8aa3b, v196
	v_mul_f32_e32 v197, 0xbfb8aa3b, v197
	v_exp_f32_e32 v190, v190
	v_exp_f32_e32 v191, v191
	v_exp_f32_e32 v192, v192
	v_exp_f32_e32 v193, v193
	v_exp_f32_e32 v194, v194
	v_exp_f32_e32 v195, v195
	v_exp_f32_e32 v196, v196
	v_exp_f32_e32 v197, v197
	v_add_f32_e32 v190, 1.0, v190
	v_add_f32_e32 v191, 1.0, v191
	v_add_f32_e32 v192, 1.0, v192
	v_add_f32_e32 v193, 1.0, v193
	v_add_f32_e32 v194, 1.0, v194
	v_add_f32_e32 v195, 1.0, v195
	v_add_f32_e32 v196, 1.0, v196
	v_add_f32_e32 v197, 1.0, v197
	v_rcp_f32_e32 v190, v190
	v_rcp_f32_e32 v191, v191
	v_rcp_f32_e32 v192, v192
	v_rcp_f32_e32 v193, v193
	v_rcp_f32_e32 v194, v194
	v_rcp_f32_e32 v195, v195
	v_rcp_f32_e32 v196, v196
	v_rcp_f32_e32 v197, v197
	v_lshlrev_b32_e32 v200, 16, v226
	v_and_b32_e32 v201, 0xffff0000, v226
	v_lshlrev_b32_e32 v202, 16, v227
	v_and_b32_e32 v203, 0xffff0000, v227
	v_lshlrev_b32_e32 v182, 16, v228
	v_and_b32_e32 v183, 0xffff0000, v228
	v_lshlrev_b32_e32 v184, 16, v229
	v_and_b32_e32 v185, 0xffff0000, v229
	v_mul_f32_e32 v200, v190, v200
	v_mul_f32_e32 v201, v191, v201
	v_mul_f32_e32 v202, v192, v202
	v_mul_f32_e32 v203, v193, v203
	v_mul_f32_e32 v182, v194, v182
	v_mul_f32_e32 v183, v195, v183
	v_mul_f32_e32 v184, v196, v184
	v_mul_f32_e32 v185, v197, v185
	v_cvt_pk_bf16_f32 v190, v200, v201
	v_cvt_pk_bf16_f32 v191, v202, v203
	v_cvt_pk_bf16_f32 v192, v182, v183
	v_cvt_pk_bf16_f32 v193, v184, v185
	s_nop 1
	global_store_dwordx4 v[168:169], v[190:193], off offset:1536
	global_load_dwordx4 v[226:229], v[140:141], off offset:256
	s_waitcnt vmcnt(8)
	v_add_f32_e32 v190, v110, v134
	v_add_f32_e32 v191, v111, v135
	v_add_f32_e32 v192, v112, v136
	v_add_f32_e32 v193, v113, v137
	v_add_f32_e32 v194, v106, v130
	v_add_f32_e32 v195, v107, v131
	v_add_f32_e32 v196, v108, v132
	v_add_f32_e32 v197, v109, v133
	v_mul_f32_e32 v190, 0xbfb8aa3b, v190
	v_mul_f32_e32 v191, 0xbfb8aa3b, v191
	v_mul_f32_e32 v192, 0xbfb8aa3b, v192
	v_mul_f32_e32 v193, 0xbfb8aa3b, v193
	v_mul_f32_e32 v194, 0xbfb8aa3b, v194
	v_mul_f32_e32 v195, 0xbfb8aa3b, v195
	v_mul_f32_e32 v196, 0xbfb8aa3b, v196
	v_mul_f32_e32 v197, 0xbfb8aa3b, v197
	v_exp_f32_e32 v190, v190
	v_exp_f32_e32 v191, v191
	v_exp_f32_e32 v192, v192
	v_exp_f32_e32 v193, v193
	v_exp_f32_e32 v194, v194
	v_exp_f32_e32 v195, v195
	v_exp_f32_e32 v196, v196
	v_exp_f32_e32 v197, v197
	v_add_f32_e32 v190, 1.0, v190
	v_add_f32_e32 v191, 1.0, v191
	v_add_f32_e32 v192, 1.0, v192
	v_add_f32_e32 v193, 1.0, v193
	v_add_f32_e32 v194, 1.0, v194
	v_add_f32_e32 v195, 1.0, v195
	v_add_f32_e32 v196, 1.0, v196
	v_add_f32_e32 v197, 1.0, v197
	v_rcp_f32_e32 v190, v190
	v_rcp_f32_e32 v191, v191
	v_rcp_f32_e32 v192, v192
	v_rcp_f32_e32 v193, v193
	v_rcp_f32_e32 v194, v194
	v_rcp_f32_e32 v195, v195
	v_rcp_f32_e32 v196, v196
	v_rcp_f32_e32 v197, v197
	v_lshlrev_b32_e32 v200, 16, v230
	v_and_b32_e32 v201, 0xffff0000, v230
	v_lshlrev_b32_e32 v202, 16, v231
	v_and_b32_e32 v203, 0xffff0000, v231
	v_lshlrev_b32_e32 v182, 16, v232
	v_and_b32_e32 v183, 0xffff0000, v232
	v_lshlrev_b32_e32 v184, 16, v233
	v_and_b32_e32 v185, 0xffff0000, v233
	v_mul_f32_e32 v200, v190, v200
	v_mul_f32_e32 v201, v191, v201
	v_mul_f32_e32 v202, v192, v202
	v_mul_f32_e32 v203, v193, v203
	v_mul_f32_e32 v182, v194, v182
	v_mul_f32_e32 v183, v195, v183
	v_mul_f32_e32 v184, v196, v184
	v_mul_f32_e32 v185, v197, v185
	v_cvt_pk_bf16_f32 v190, v200, v201
	v_cvt_pk_bf16_f32 v191, v202, v203
	v_cvt_pk_bf16_f32 v192, v182, v183
	v_cvt_pk_bf16_f32 v193, v184, v185
	s_mov_b64 s[10:11], 0x8000
	v_lshl_add_u64 v[242:243], v[168:169], 0, s[10:11]
	global_store_dwordx4 v[242:243], v[190:193], off offset:1536
	s_mov_b64 s[10:11], 0x2000
	v_lshl_add_u64 v[198:199], v[140:141], 0, s[10:11]
	global_load_dwordx4 v[230:233], v[198:199], off offset:256
	s_waitcnt vmcnt(9)
	v_add_f32_e32 v190, v94, v134
	v_add_f32_e32 v191, v95, v135
	v_add_f32_e32 v192, v96, v136
	v_add_f32_e32 v193, v97, v137
	v_add_f32_e32 v194, v90, v130
	v_add_f32_e32 v195, v91, v131
	v_add_f32_e32 v196, v92, v132
	v_add_f32_e32 v197, v93, v133
	v_mul_f32_e32 v190, 0xbfb8aa3b, v190
	v_mul_f32_e32 v191, 0xbfb8aa3b, v191
	v_mul_f32_e32 v192, 0xbfb8aa3b, v192
	v_mul_f32_e32 v193, 0xbfb8aa3b, v193
	v_mul_f32_e32 v194, 0xbfb8aa3b, v194
	v_mul_f32_e32 v195, 0xbfb8aa3b, v195
	v_mul_f32_e32 v196, 0xbfb8aa3b, v196
	v_mul_f32_e32 v197, 0xbfb8aa3b, v197
	v_exp_f32_e32 v190, v190
	v_exp_f32_e32 v191, v191
	v_exp_f32_e32 v192, v192
	v_exp_f32_e32 v193, v193
	v_exp_f32_e32 v194, v194
	v_exp_f32_e32 v195, v195
	v_exp_f32_e32 v196, v196
	v_exp_f32_e32 v197, v197
	v_add_f32_e32 v190, 1.0, v190
	v_add_f32_e32 v191, 1.0, v191
	v_add_f32_e32 v192, 1.0, v192
	v_add_f32_e32 v193, 1.0, v193
	v_add_f32_e32 v194, 1.0, v194
	v_add_f32_e32 v195, 1.0, v195
	v_add_f32_e32 v196, 1.0, v196
	v_add_f32_e32 v197, 1.0, v197
	v_rcp_f32_e32 v190, v190
	v_rcp_f32_e32 v191, v191
	v_rcp_f32_e32 v192, v192
	v_rcp_f32_e32 v193, v193
	v_rcp_f32_e32 v194, v194
	v_rcp_f32_e32 v195, v195
	v_rcp_f32_e32 v196, v196
	v_rcp_f32_e32 v197, v197
	v_lshlrev_b32_e32 v200, 16, v234
	v_and_b32_e32 v201, 0xffff0000, v234
	v_lshlrev_b32_e32 v202, 16, v235
	v_and_b32_e32 v203, 0xffff0000, v235
	v_lshlrev_b32_e32 v182, 16, v236
	v_and_b32_e32 v183, 0xffff0000, v236
	v_lshlrev_b32_e32 v184, 16, v237
	v_and_b32_e32 v185, 0xffff0000, v237
	v_mul_f32_e32 v200, v190, v200
	v_mul_f32_e32 v201, v191, v201
	v_mul_f32_e32 v202, v192, v202
	v_mul_f32_e32 v203, v193, v203
	v_mul_f32_e32 v182, v194, v182
	v_mul_f32_e32 v183, v195, v183
	v_mul_f32_e32 v184, v196, v184
	v_mul_f32_e32 v185, v197, v185
	v_cvt_pk_bf16_f32 v190, v200, v201
	v_cvt_pk_bf16_f32 v191, v202, v203
	v_cvt_pk_bf16_f32 v192, v182, v183
	v_cvt_pk_bf16_f32 v193, v184, v185
	s_mov_b64 s[10:11], 0x10000
	v_lshl_add_u64 v[242:243], v[168:169], 0, s[10:11]
	global_store_dwordx4 v[242:243], v[190:193], off offset:1536
	s_mov_b64 s[10:11], 0x4000
	v_lshl_add_u64 v[198:199], v[140:141], 0, s[10:11]
	global_load_dwordx4 v[234:237], v[198:199], off offset:256
	s_waitcnt vmcnt(10)
	v_add_f32_e32 v190, v78, v134
	v_add_f32_e32 v191, v79, v135
	v_add_f32_e32 v192, v80, v136
	v_add_f32_e32 v193, v81, v137
	v_add_f32_e32 v194, v74, v130
	v_add_f32_e32 v195, v75, v131
	v_add_f32_e32 v196, v76, v132
	v_add_f32_e32 v197, v77, v133
	v_mul_f32_e32 v190, 0xbfb8aa3b, v190
	v_mul_f32_e32 v191, 0xbfb8aa3b, v191
	v_mul_f32_e32 v192, 0xbfb8aa3b, v192
	v_mul_f32_e32 v193, 0xbfb8aa3b, v193
	v_mul_f32_e32 v194, 0xbfb8aa3b, v194
	v_mul_f32_e32 v195, 0xbfb8aa3b, v195
	v_mul_f32_e32 v196, 0xbfb8aa3b, v196
	v_mul_f32_e32 v197, 0xbfb8aa3b, v197
	v_exp_f32_e32 v190, v190
	v_exp_f32_e32 v191, v191
	v_exp_f32_e32 v192, v192
	v_exp_f32_e32 v193, v193
	v_exp_f32_e32 v194, v194
	v_exp_f32_e32 v195, v195
	v_exp_f32_e32 v196, v196
	v_exp_f32_e32 v197, v197
	v_add_f32_e32 v190, 1.0, v190
	v_add_f32_e32 v191, 1.0, v191
	v_add_f32_e32 v192, 1.0, v192
	v_add_f32_e32 v193, 1.0, v193
	v_add_f32_e32 v194, 1.0, v194
	v_add_f32_e32 v195, 1.0, v195
	v_add_f32_e32 v196, 1.0, v196
	v_add_f32_e32 v197, 1.0, v197
	v_rcp_f32_e32 v190, v190
	v_rcp_f32_e32 v191, v191
	v_rcp_f32_e32 v192, v192
	v_rcp_f32_e32 v193, v193
	v_rcp_f32_e32 v194, v194
	v_rcp_f32_e32 v195, v195
	v_rcp_f32_e32 v196, v196
	v_rcp_f32_e32 v197, v197
	v_lshlrev_b32_e32 v200, 16, v238
	v_and_b32_e32 v201, 0xffff0000, v238
	v_lshlrev_b32_e32 v202, 16, v239
	v_and_b32_e32 v203, 0xffff0000, v239
	v_lshlrev_b32_e32 v182, 16, v240
	v_and_b32_e32 v183, 0xffff0000, v240
	v_lshlrev_b32_e32 v184, 16, v241
	v_and_b32_e32 v185, 0xffff0000, v241
	v_mul_f32_e32 v200, v190, v200
	v_mul_f32_e32 v201, v191, v201
	v_mul_f32_e32 v202, v192, v202
	v_mul_f32_e32 v203, v193, v203
	v_mul_f32_e32 v182, v194, v182
	v_mul_f32_e32 v183, v195, v183
	v_mul_f32_e32 v184, v196, v184
	v_mul_f32_e32 v185, v197, v185
	v_cvt_pk_bf16_f32 v190, v200, v201
	v_cvt_pk_bf16_f32 v191, v202, v203
	v_cvt_pk_bf16_f32 v192, v182, v183
	v_cvt_pk_bf16_f32 v193, v184, v185
	s_mov_b64 s[10:11], 0x18000
	v_lshl_add_u64 v[242:243], v[168:169], 0, s[10:11]
	global_store_dwordx4 v[242:243], v[190:193], off offset:1536
	s_mov_b64 s[10:11], 0x6000
	v_lshl_add_u64 v[198:199], v[140:141], 0, s[10:11]
	global_load_dwordx4 v[238:241], v[198:199], off offset:256
	s_waitcnt vmcnt(11)
	v_add_f32_e32 v190, v62, v134
	v_add_f32_e32 v191, v63, v135
	v_add_f32_e32 v192, v64, v136
	v_add_f32_e32 v193, v65, v137
	v_add_f32_e32 v194, v58, v130
	v_add_f32_e32 v195, v59, v131
	v_add_f32_e32 v196, v60, v132
	v_add_f32_e32 v197, v61, v133
	v_mul_f32_e32 v190, 0xbfb8aa3b, v190
	v_mul_f32_e32 v191, 0xbfb8aa3b, v191
	v_mul_f32_e32 v192, 0xbfb8aa3b, v192
	v_mul_f32_e32 v193, 0xbfb8aa3b, v193
	v_mul_f32_e32 v194, 0xbfb8aa3b, v194
	v_mul_f32_e32 v195, 0xbfb8aa3b, v195
	v_mul_f32_e32 v196, 0xbfb8aa3b, v196
	v_mul_f32_e32 v197, 0xbfb8aa3b, v197
	v_exp_f32_e32 v190, v190
	v_exp_f32_e32 v191, v191
	v_exp_f32_e32 v192, v192
	v_exp_f32_e32 v193, v193
	v_exp_f32_e32 v194, v194
	v_exp_f32_e32 v195, v195
	v_exp_f32_e32 v196, v196
	v_exp_f32_e32 v197, v197
	v_add_f32_e32 v190, 1.0, v190
	v_add_f32_e32 v191, 1.0, v191
	v_add_f32_e32 v192, 1.0, v192
	v_add_f32_e32 v193, 1.0, v193
	v_add_f32_e32 v194, 1.0, v194
	v_add_f32_e32 v195, 1.0, v195
	v_add_f32_e32 v196, 1.0, v196
	v_add_f32_e32 v197, 1.0, v197
	v_rcp_f32_e32 v190, v190
	v_rcp_f32_e32 v191, v191
	v_rcp_f32_e32 v192, v192
	v_rcp_f32_e32 v193, v193
	v_rcp_f32_e32 v194, v194
	v_rcp_f32_e32 v195, v195
	v_rcp_f32_e32 v196, v196
	v_rcp_f32_e32 v197, v197
	v_lshlrev_b32_e32 v200, 16, v170
	v_and_b32_e32 v201, 0xffff0000, v170
	v_lshlrev_b32_e32 v202, 16, v171
	v_and_b32_e32 v203, 0xffff0000, v171
	v_lshlrev_b32_e32 v182, 16, v172
	v_and_b32_e32 v183, 0xffff0000, v172
	v_lshlrev_b32_e32 v184, 16, v173
	v_and_b32_e32 v185, 0xffff0000, v173
	v_mul_f32_e32 v200, v190, v200
	v_mul_f32_e32 v201, v191, v201
	v_mul_f32_e32 v202, v192, v202
	v_mul_f32_e32 v203, v193, v203
	v_mul_f32_e32 v182, v194, v182
	v_mul_f32_e32 v183, v195, v183
	v_mul_f32_e32 v184, v196, v184
	v_mul_f32_e32 v185, v197, v185
	v_cvt_pk_bf16_f32 v190, v200, v201
	v_cvt_pk_bf16_f32 v191, v202, v203
	v_cvt_pk_bf16_f32 v192, v182, v183
	v_cvt_pk_bf16_f32 v193, v184, v185
	s_mov_b64 s[10:11], 0x40000
	v_lshl_add_u64 v[242:243], v[168:169], 0, s[10:11]
	global_store_dwordx4 v[242:243], v[190:193], off offset:1536
	s_mov_b64 s[10:11], 0x10000
	v_lshl_add_u64 v[198:199], v[140:141], 0, s[10:11]
	global_load_dwordx4 v[170:173], v[198:199], off offset:256
	s_waitcnt vmcnt(12)
	v_add_f32_e32 v190, v46, v134
	v_add_f32_e32 v191, v47, v135
	v_add_f32_e32 v192, v48, v136
	v_add_f32_e32 v193, v49, v137
	v_add_f32_e32 v194, v42, v130
	v_add_f32_e32 v195, v43, v131
	v_add_f32_e32 v196, v44, v132
	v_add_f32_e32 v197, v45, v133
	v_mul_f32_e32 v190, 0xbfb8aa3b, v190
	v_mul_f32_e32 v191, 0xbfb8aa3b, v191
	v_mul_f32_e32 v192, 0xbfb8aa3b, v192
	v_mul_f32_e32 v193, 0xbfb8aa3b, v193
	v_mul_f32_e32 v194, 0xbfb8aa3b, v194
	v_mul_f32_e32 v195, 0xbfb8aa3b, v195
	v_mul_f32_e32 v196, 0xbfb8aa3b, v196
	v_mul_f32_e32 v197, 0xbfb8aa3b, v197
	v_exp_f32_e32 v190, v190
	v_exp_f32_e32 v191, v191
	v_exp_f32_e32 v192, v192
	v_exp_f32_e32 v193, v193
	v_exp_f32_e32 v194, v194
	v_exp_f32_e32 v195, v195
	v_exp_f32_e32 v196, v196
	v_exp_f32_e32 v197, v197
	v_add_f32_e32 v190, 1.0, v190
	v_add_f32_e32 v191, 1.0, v191
	v_add_f32_e32 v192, 1.0, v192
	v_add_f32_e32 v193, 1.0, v193
	v_add_f32_e32 v194, 1.0, v194
	v_add_f32_e32 v195, 1.0, v195
	v_add_f32_e32 v196, 1.0, v196
	v_add_f32_e32 v197, 1.0, v197
	v_rcp_f32_e32 v190, v190
	v_rcp_f32_e32 v191, v191
	v_rcp_f32_e32 v192, v192
	v_rcp_f32_e32 v193, v193
	v_rcp_f32_e32 v194, v194
	v_rcp_f32_e32 v195, v195
	v_rcp_f32_e32 v196, v196
	v_rcp_f32_e32 v197, v197
	v_lshlrev_b32_e32 v200, 16, v174
	v_and_b32_e32 v201, 0xffff0000, v174
	v_lshlrev_b32_e32 v202, 16, v175
	v_and_b32_e32 v203, 0xffff0000, v175
	v_lshlrev_b32_e32 v182, 16, v176
	v_and_b32_e32 v183, 0xffff0000, v176
	v_lshlrev_b32_e32 v184, 16, v177
	v_and_b32_e32 v185, 0xffff0000, v177
	v_mul_f32_e32 v200, v190, v200
	v_mul_f32_e32 v201, v191, v201
	v_mul_f32_e32 v202, v192, v202
	v_mul_f32_e32 v203, v193, v203
	v_mul_f32_e32 v182, v194, v182
	v_mul_f32_e32 v183, v195, v183
	v_mul_f32_e32 v184, v196, v184
	v_mul_f32_e32 v185, v197, v185
	v_cvt_pk_bf16_f32 v190, v200, v201
	v_cvt_pk_bf16_f32 v191, v202, v203
	v_cvt_pk_bf16_f32 v192, v182, v183
	v_cvt_pk_bf16_f32 v193, v184, v185
	s_mov_b64 s[10:11], 0x48000
	v_lshl_add_u64 v[242:243], v[168:169], 0, s[10:11]
	global_store_dwordx4 v[242:243], v[190:193], off offset:1536
	s_mov_b64 s[10:11], 0x12000
	v_lshl_add_u64 v[198:199], v[140:141], 0, s[10:11]
	global_load_dwordx4 v[174:177], v[198:199], off offset:256
	s_waitcnt vmcnt(13)
	v_add_f32_e32 v190, v30, v134
	v_add_f32_e32 v191, v31, v135
	v_add_f32_e32 v192, v32, v136
	v_add_f32_e32 v193, v33, v137
	v_add_f32_e32 v194, v26, v130
	v_add_f32_e32 v195, v27, v131
	v_add_f32_e32 v196, v28, v132
	v_add_f32_e32 v197, v29, v133
	v_mul_f32_e32 v190, 0xbfb8aa3b, v190
	v_mul_f32_e32 v191, 0xbfb8aa3b, v191
	v_mul_f32_e32 v192, 0xbfb8aa3b, v192
	v_mul_f32_e32 v193, 0xbfb8aa3b, v193
	v_mul_f32_e32 v194, 0xbfb8aa3b, v194
	v_mul_f32_e32 v195, 0xbfb8aa3b, v195
	v_mul_f32_e32 v196, 0xbfb8aa3b, v196
	v_mul_f32_e32 v197, 0xbfb8aa3b, v197
	v_exp_f32_e32 v190, v190
	v_exp_f32_e32 v191, v191
	v_exp_f32_e32 v192, v192
	v_exp_f32_e32 v193, v193
	v_exp_f32_e32 v194, v194
	v_exp_f32_e32 v195, v195
	v_exp_f32_e32 v196, v196
	v_exp_f32_e32 v197, v197
	v_add_f32_e32 v190, 1.0, v190
	v_add_f32_e32 v191, 1.0, v191
	v_add_f32_e32 v192, 1.0, v192
	v_add_f32_e32 v193, 1.0, v193
	v_add_f32_e32 v194, 1.0, v194
	v_add_f32_e32 v195, 1.0, v195
	v_add_f32_e32 v196, 1.0, v196
	v_add_f32_e32 v197, 1.0, v197
	v_rcp_f32_e32 v190, v190
	v_rcp_f32_e32 v191, v191
	v_rcp_f32_e32 v192, v192
	v_rcp_f32_e32 v193, v193
	v_rcp_f32_e32 v194, v194
	v_rcp_f32_e32 v195, v195
	v_rcp_f32_e32 v196, v196
	v_rcp_f32_e32 v197, v197
	v_lshlrev_b32_e32 v200, 16, v178
	v_and_b32_e32 v201, 0xffff0000, v178
	v_lshlrev_b32_e32 v202, 16, v179
	v_and_b32_e32 v203, 0xffff0000, v179
	v_lshlrev_b32_e32 v182, 16, v180
	v_and_b32_e32 v183, 0xffff0000, v180
	v_lshlrev_b32_e32 v184, 16, v181
	v_and_b32_e32 v185, 0xffff0000, v181
	v_mul_f32_e32 v200, v190, v200
	v_mul_f32_e32 v201, v191, v201
	v_mul_f32_e32 v202, v192, v202
	v_mul_f32_e32 v203, v193, v203
	v_mul_f32_e32 v182, v194, v182
	v_mul_f32_e32 v183, v195, v183
	v_mul_f32_e32 v184, v196, v184
	v_mul_f32_e32 v185, v197, v185
	v_cvt_pk_bf16_f32 v190, v200, v201
	v_cvt_pk_bf16_f32 v191, v202, v203
	v_cvt_pk_bf16_f32 v192, v182, v183
	v_cvt_pk_bf16_f32 v193, v184, v185
	s_mov_b64 s[10:11], 0x50000
	v_lshl_add_u64 v[242:243], v[168:169], 0, s[10:11]
	global_store_dwordx4 v[242:243], v[190:193], off offset:1536
	s_mov_b64 s[10:11], 0x14000
	v_lshl_add_u64 v[198:199], v[140:141], 0, s[10:11]
	global_load_dwordx4 v[178:181], v[198:199], off offset:256
	s_waitcnt vmcnt(14)
	v_add_f32_e32 v190, v14, v134
	v_add_f32_e32 v191, v15, v135
	v_add_f32_e32 v192, v16, v136
	v_add_f32_e32 v193, v17, v137
	v_add_f32_e32 v194, v10, v130
	v_add_f32_e32 v195, v11, v131
	v_add_f32_e32 v196, v12, v132
	v_add_f32_e32 v197, v13, v133
	v_mul_f32_e32 v190, 0xbfb8aa3b, v190
	v_mul_f32_e32 v191, 0xbfb8aa3b, v191
	v_mul_f32_e32 v192, 0xbfb8aa3b, v192
	v_mul_f32_e32 v193, 0xbfb8aa3b, v193
	v_mul_f32_e32 v194, 0xbfb8aa3b, v194
	v_mul_f32_e32 v195, 0xbfb8aa3b, v195
	v_mul_f32_e32 v196, 0xbfb8aa3b, v196
	v_mul_f32_e32 v197, 0xbfb8aa3b, v197
	v_exp_f32_e32 v190, v190
	v_exp_f32_e32 v191, v191
	v_exp_f32_e32 v192, v192
	v_exp_f32_e32 v193, v193
	v_exp_f32_e32 v194, v194
	v_exp_f32_e32 v195, v195
	v_exp_f32_e32 v196, v196
	v_exp_f32_e32 v197, v197
	v_add_f32_e32 v190, 1.0, v190
	v_add_f32_e32 v191, 1.0, v191
	v_add_f32_e32 v192, 1.0, v192
	v_add_f32_e32 v193, 1.0, v193
	v_add_f32_e32 v194, 1.0, v194
	v_add_f32_e32 v195, 1.0, v195
	v_add_f32_e32 v196, 1.0, v196
	v_add_f32_e32 v197, 1.0, v197
	v_rcp_f32_e32 v190, v190
	v_rcp_f32_e32 v191, v191
	v_rcp_f32_e32 v192, v192
	v_rcp_f32_e32 v193, v193
	v_rcp_f32_e32 v194, v194
	v_rcp_f32_e32 v195, v195
	v_rcp_f32_e32 v196, v196
	v_rcp_f32_e32 v197, v197
	v_lshlrev_b32_e32 v200, 16, v186
	v_and_b32_e32 v201, 0xffff0000, v186
	v_lshlrev_b32_e32 v202, 16, v187
	v_and_b32_e32 v203, 0xffff0000, v187
	v_lshlrev_b32_e32 v182, 16, v188
	v_and_b32_e32 v183, 0xffff0000, v188
	v_lshlrev_b32_e32 v184, 16, v189
	v_and_b32_e32 v185, 0xffff0000, v189
	v_mul_f32_e32 v200, v190, v200
	v_mul_f32_e32 v201, v191, v201
	v_mul_f32_e32 v202, v192, v202
	v_mul_f32_e32 v203, v193, v203
	v_mul_f32_e32 v182, v194, v182
	v_mul_f32_e32 v183, v195, v183
	v_mul_f32_e32 v184, v196, v184
	v_mul_f32_e32 v185, v197, v185
	v_cvt_pk_bf16_f32 v190, v200, v201
	v_cvt_pk_bf16_f32 v191, v202, v203
	v_cvt_pk_bf16_f32 v192, v182, v183
	v_cvt_pk_bf16_f32 v193, v184, v185
	s_mov_b64 s[10:11], 0x58000
	v_lshl_add_u64 v[242:243], v[168:169], 0, s[10:11]
	global_store_dwordx4 v[242:243], v[190:193], off offset:1536
	s_mov_b64 s[10:11], 0x16000
	v_lshl_add_u64 v[198:199], v[140:141], 0, s[10:11]
	global_load_dwordx4 v[186:189], v[198:199], off offset:256
	s_waitcnt vmcnt(14)
	v_add_f32_e32 v190, v118, v160
	v_add_f32_e32 v191, v119, v161
	v_add_f32_e32 v192, v120, v162
	v_add_f32_e32 v193, v121, v163
	v_add_f32_e32 v194, v114, v164
	v_add_f32_e32 v195, v115, v165
	v_add_f32_e32 v196, v116, v166
	v_add_f32_e32 v197, v117, v167
	v_mul_f32_e32 v190, 0xbfb8aa3b, v190
	v_mul_f32_e32 v191, 0xbfb8aa3b, v191
	v_mul_f32_e32 v192, 0xbfb8aa3b, v192
	v_mul_f32_e32 v193, 0xbfb8aa3b, v193
	v_mul_f32_e32 v194, 0xbfb8aa3b, v194
	v_mul_f32_e32 v195, 0xbfb8aa3b, v195
	v_mul_f32_e32 v196, 0xbfb8aa3b, v196
	v_mul_f32_e32 v197, 0xbfb8aa3b, v197
	v_exp_f32_e32 v190, v190
	v_exp_f32_e32 v191, v191
	v_exp_f32_e32 v192, v192
	v_exp_f32_e32 v193, v193
	v_exp_f32_e32 v194, v194
	v_exp_f32_e32 v195, v195
	v_exp_f32_e32 v196, v196
	v_exp_f32_e32 v197, v197
	v_add_f32_e32 v190, 1.0, v190
	v_add_f32_e32 v191, 1.0, v191
	v_add_f32_e32 v192, 1.0, v192
	v_add_f32_e32 v193, 1.0, v193
	v_add_f32_e32 v194, 1.0, v194
	v_add_f32_e32 v195, 1.0, v195
	v_add_f32_e32 v196, 1.0, v196
	v_add_f32_e32 v197, 1.0, v197
	v_rcp_f32_e32 v190, v190
	v_rcp_f32_e32 v191, v191
	v_rcp_f32_e32 v192, v192
	v_rcp_f32_e32 v193, v193
	v_rcp_f32_e32 v194, v194
	v_rcp_f32_e32 v195, v195
	v_rcp_f32_e32 v196, v196
	v_rcp_f32_e32 v197, v197
	v_lshlrev_b32_e32 v200, 16, v226
	v_and_b32_e32 v201, 0xffff0000, v226
	v_lshlrev_b32_e32 v202, 16, v227
	v_and_b32_e32 v203, 0xffff0000, v227
	v_lshlrev_b32_e32 v182, 16, v228
	v_and_b32_e32 v183, 0xffff0000, v228
	v_lshlrev_b32_e32 v184, 16, v229
	v_and_b32_e32 v185, 0xffff0000, v229
	v_mul_f32_e32 v200, v190, v200
	v_mul_f32_e32 v201, v191, v201
	v_mul_f32_e32 v202, v192, v202
	v_mul_f32_e32 v203, v193, v203
	v_mul_f32_e32 v182, v194, v182
	v_mul_f32_e32 v183, v195, v183
	v_mul_f32_e32 v184, v196, v184
	v_mul_f32_e32 v185, v197, v185
	v_cvt_pk_bf16_f32 v190, v200, v201
	v_cvt_pk_bf16_f32 v191, v202, v203
	v_cvt_pk_bf16_f32 v192, v182, v183
	v_cvt_pk_bf16_f32 v193, v184, v185
	s_nop 1
	global_store_dwordx4 v[168:169], v[190:193], off offset:1792
	s_nop 1
	s_waitcnt vmcnt(13)
	v_add_f32_e32 v190, v102, v160
	v_add_f32_e32 v191, v103, v161
	v_add_f32_e32 v192, v104, v162
	v_add_f32_e32 v193, v105, v163
	v_add_f32_e32 v194, v98, v164
	v_add_f32_e32 v195, v99, v165
	v_add_f32_e32 v196, v100, v166
	v_add_f32_e32 v197, v101, v167
	v_mul_f32_e32 v190, 0xbfb8aa3b, v190
	v_mul_f32_e32 v191, 0xbfb8aa3b, v191
	v_mul_f32_e32 v192, 0xbfb8aa3b, v192
	v_mul_f32_e32 v193, 0xbfb8aa3b, v193
	v_mul_f32_e32 v194, 0xbfb8aa3b, v194
	v_mul_f32_e32 v195, 0xbfb8aa3b, v195
	v_mul_f32_e32 v196, 0xbfb8aa3b, v196
	v_mul_f32_e32 v197, 0xbfb8aa3b, v197
	v_exp_f32_e32 v190, v190
	v_exp_f32_e32 v191, v191
	v_exp_f32_e32 v192, v192
	v_exp_f32_e32 v193, v193
	v_exp_f32_e32 v194, v194
	v_exp_f32_e32 v195, v195
	v_exp_f32_e32 v196, v196
	v_exp_f32_e32 v197, v197
	v_add_f32_e32 v190, 1.0, v190
	v_add_f32_e32 v191, 1.0, v191
	v_add_f32_e32 v192, 1.0, v192
	v_add_f32_e32 v193, 1.0, v193
	v_add_f32_e32 v194, 1.0, v194
	v_add_f32_e32 v195, 1.0, v195
	v_add_f32_e32 v196, 1.0, v196
	v_add_f32_e32 v197, 1.0, v197
	v_rcp_f32_e32 v190, v190
	v_rcp_f32_e32 v191, v191
	v_rcp_f32_e32 v192, v192
	v_rcp_f32_e32 v193, v193
	v_rcp_f32_e32 v194, v194
	v_rcp_f32_e32 v195, v195
	v_rcp_f32_e32 v196, v196
	v_rcp_f32_e32 v197, v197
	v_lshlrev_b32_e32 v200, 16, v230
	v_and_b32_e32 v201, 0xffff0000, v230
	v_lshlrev_b32_e32 v202, 16, v231
	v_and_b32_e32 v203, 0xffff0000, v231
	v_lshlrev_b32_e32 v182, 16, v232
	v_and_b32_e32 v183, 0xffff0000, v232
	v_lshlrev_b32_e32 v184, 16, v233
	v_and_b32_e32 v185, 0xffff0000, v233
	v_mul_f32_e32 v200, v190, v200
	v_mul_f32_e32 v201, v191, v201
	v_mul_f32_e32 v202, v192, v202
	v_mul_f32_e32 v203, v193, v203
	v_mul_f32_e32 v182, v194, v182
	v_mul_f32_e32 v183, v195, v183
	v_mul_f32_e32 v184, v196, v184
	v_mul_f32_e32 v185, v197, v185
	v_cvt_pk_bf16_f32 v190, v200, v201
	v_cvt_pk_bf16_f32 v191, v202, v203
	v_cvt_pk_bf16_f32 v192, v182, v183
	v_cvt_pk_bf16_f32 v193, v184, v185
	s_mov_b64 s[10:11], 0x8000
	v_lshl_add_u64 v[198:199], v[168:169], 0, s[10:11]
	global_store_dwordx4 v[198:199], v[190:193], off offset:1792
	s_nop 1
	s_waitcnt vmcnt(12)
	v_add_f32_e32 v190, v86, v160
	v_add_f32_e32 v191, v87, v161
	v_add_f32_e32 v192, v88, v162
	v_add_f32_e32 v193, v89, v163
	v_add_f32_e32 v194, v82, v164
	v_add_f32_e32 v195, v83, v165
	v_add_f32_e32 v196, v84, v166
	v_add_f32_e32 v197, v85, v167
	v_mul_f32_e32 v190, 0xbfb8aa3b, v190
	v_mul_f32_e32 v191, 0xbfb8aa3b, v191
	v_mul_f32_e32 v192, 0xbfb8aa3b, v192
	v_mul_f32_e32 v193, 0xbfb8aa3b, v193
	v_mul_f32_e32 v194, 0xbfb8aa3b, v194
	v_mul_f32_e32 v195, 0xbfb8aa3b, v195
	v_mul_f32_e32 v196, 0xbfb8aa3b, v196
	v_mul_f32_e32 v197, 0xbfb8aa3b, v197
	v_exp_f32_e32 v190, v190
	v_exp_f32_e32 v191, v191
	v_exp_f32_e32 v192, v192
	v_exp_f32_e32 v193, v193
	v_exp_f32_e32 v194, v194
	v_exp_f32_e32 v195, v195
	v_exp_f32_e32 v196, v196
	v_exp_f32_e32 v197, v197
	v_add_f32_e32 v190, 1.0, v190
	v_add_f32_e32 v191, 1.0, v191
	v_add_f32_e32 v192, 1.0, v192
	v_add_f32_e32 v193, 1.0, v193
	v_add_f32_e32 v194, 1.0, v194
	v_add_f32_e32 v195, 1.0, v195
	v_add_f32_e32 v196, 1.0, v196
	v_add_f32_e32 v197, 1.0, v197
	v_rcp_f32_e32 v190, v190
	v_rcp_f32_e32 v191, v191
	v_rcp_f32_e32 v192, v192
	v_rcp_f32_e32 v193, v193
	v_rcp_f32_e32 v194, v194
	v_rcp_f32_e32 v195, v195
	v_rcp_f32_e32 v196, v196
	v_rcp_f32_e32 v197, v197
	v_lshlrev_b32_e32 v200, 16, v234
	v_and_b32_e32 v201, 0xffff0000, v234
	v_lshlrev_b32_e32 v202, 16, v235
	v_and_b32_e32 v203, 0xffff0000, v235
	v_lshlrev_b32_e32 v182, 16, v236
	v_and_b32_e32 v183, 0xffff0000, v236
	v_lshlrev_b32_e32 v184, 16, v237
	v_and_b32_e32 v185, 0xffff0000, v237
	v_mul_f32_e32 v200, v190, v200
	v_mul_f32_e32 v201, v191, v201
	v_mul_f32_e32 v202, v192, v202
	v_mul_f32_e32 v203, v193, v203
	v_mul_f32_e32 v182, v194, v182
	v_mul_f32_e32 v183, v195, v183
	v_mul_f32_e32 v184, v196, v184
	v_mul_f32_e32 v185, v197, v185
	v_cvt_pk_bf16_f32 v190, v200, v201
	v_cvt_pk_bf16_f32 v191, v202, v203
	v_cvt_pk_bf16_f32 v192, v182, v183
	v_cvt_pk_bf16_f32 v193, v184, v185
	s_mov_b64 s[10:11], 0x10000
	v_lshl_add_u64 v[242:243], v[168:169], 0, s[10:11]
	global_store_dwordx4 v[242:243], v[190:193], off offset:1792
	s_nop 1
	s_waitcnt vmcnt(11)
	v_add_f32_e32 v190, v70, v160
	v_add_f32_e32 v191, v71, v161
	v_add_f32_e32 v192, v72, v162
	v_add_f32_e32 v193, v73, v163
	v_add_f32_e32 v194, v66, v164
	v_add_f32_e32 v195, v67, v165
	v_add_f32_e32 v196, v68, v166
	v_add_f32_e32 v197, v69, v167
	v_mul_f32_e32 v190, 0xbfb8aa3b, v190
	v_mul_f32_e32 v191, 0xbfb8aa3b, v191
	v_mul_f32_e32 v192, 0xbfb8aa3b, v192
	v_mul_f32_e32 v193, 0xbfb8aa3b, v193
	v_mul_f32_e32 v194, 0xbfb8aa3b, v194
	v_mul_f32_e32 v195, 0xbfb8aa3b, v195
	v_mul_f32_e32 v196, 0xbfb8aa3b, v196
	v_mul_f32_e32 v197, 0xbfb8aa3b, v197
	v_exp_f32_e32 v190, v190
	v_exp_f32_e32 v191, v191
	v_exp_f32_e32 v192, v192
	v_exp_f32_e32 v193, v193
	v_exp_f32_e32 v194, v194
	v_exp_f32_e32 v195, v195
	v_exp_f32_e32 v196, v196
	v_exp_f32_e32 v197, v197
	v_add_f32_e32 v190, 1.0, v190
	v_add_f32_e32 v191, 1.0, v191
	v_add_f32_e32 v192, 1.0, v192
	v_add_f32_e32 v193, 1.0, v193
	v_add_f32_e32 v194, 1.0, v194
	v_add_f32_e32 v195, 1.0, v195
	v_add_f32_e32 v196, 1.0, v196
	v_add_f32_e32 v197, 1.0, v197
	v_rcp_f32_e32 v190, v190
	v_rcp_f32_e32 v191, v191
	v_rcp_f32_e32 v192, v192
	v_rcp_f32_e32 v193, v193
	v_rcp_f32_e32 v194, v194
	v_rcp_f32_e32 v195, v195
	v_rcp_f32_e32 v196, v196
	v_rcp_f32_e32 v197, v197
	v_lshlrev_b32_e32 v200, 16, v238
	v_and_b32_e32 v201, 0xffff0000, v238
	v_lshlrev_b32_e32 v202, 16, v239
	v_and_b32_e32 v203, 0xffff0000, v239
	v_lshlrev_b32_e32 v182, 16, v240
	v_and_b32_e32 v183, 0xffff0000, v240
	v_lshlrev_b32_e32 v184, 16, v241
	v_and_b32_e32 v185, 0xffff0000, v241
	v_mul_f32_e32 v200, v190, v200
	v_mul_f32_e32 v201, v191, v201
	v_mul_f32_e32 v202, v192, v202
	v_mul_f32_e32 v203, v193, v203
	v_mul_f32_e32 v182, v194, v182
	v_mul_f32_e32 v183, v195, v183
	v_mul_f32_e32 v184, v196, v184
	v_mul_f32_e32 v185, v197, v185
	v_cvt_pk_bf16_f32 v190, v200, v201
	v_cvt_pk_bf16_f32 v191, v202, v203
	v_cvt_pk_bf16_f32 v192, v182, v183
	v_cvt_pk_bf16_f32 v193, v184, v185
	s_mov_b64 s[10:11], 0x18000
	v_lshl_add_u64 v[198:199], v[168:169], 0, s[10:11]
	global_store_dwordx4 v[198:199], v[190:193], off offset:1792
	s_nop 1
	s_waitcnt vmcnt(10)
	v_add_f32_e32 v190, v54, v160
	v_add_f32_e32 v191, v55, v161
	v_add_f32_e32 v192, v56, v162
	v_add_f32_e32 v193, v57, v163
	v_add_f32_e32 v194, v50, v164
	v_add_f32_e32 v195, v51, v165
	v_add_f32_e32 v196, v52, v166
	v_add_f32_e32 v197, v53, v167
	v_mul_f32_e32 v190, 0xbfb8aa3b, v190
	v_mul_f32_e32 v191, 0xbfb8aa3b, v191
	v_mul_f32_e32 v192, 0xbfb8aa3b, v192
	v_mul_f32_e32 v193, 0xbfb8aa3b, v193
	v_mul_f32_e32 v194, 0xbfb8aa3b, v194
	v_mul_f32_e32 v195, 0xbfb8aa3b, v195
	v_mul_f32_e32 v196, 0xbfb8aa3b, v196
	v_mul_f32_e32 v197, 0xbfb8aa3b, v197
	v_exp_f32_e32 v190, v190
	v_exp_f32_e32 v191, v191
	v_exp_f32_e32 v192, v192
	v_exp_f32_e32 v193, v193
	v_exp_f32_e32 v194, v194
	v_exp_f32_e32 v195, v195
	v_exp_f32_e32 v196, v196
	v_exp_f32_e32 v197, v197
	v_add_f32_e32 v190, 1.0, v190
	v_add_f32_e32 v191, 1.0, v191
	v_add_f32_e32 v192, 1.0, v192
	v_add_f32_e32 v193, 1.0, v193
	v_add_f32_e32 v194, 1.0, v194
	v_add_f32_e32 v195, 1.0, v195
	v_add_f32_e32 v196, 1.0, v196
	v_add_f32_e32 v197, 1.0, v197
	v_rcp_f32_e32 v190, v190
	v_rcp_f32_e32 v191, v191
	v_rcp_f32_e32 v192, v192
	v_rcp_f32_e32 v193, v193
	v_rcp_f32_e32 v194, v194
	v_rcp_f32_e32 v195, v195
	v_rcp_f32_e32 v196, v196
	v_rcp_f32_e32 v197, v197
	v_lshlrev_b32_e32 v200, 16, v170
	v_and_b32_e32 v201, 0xffff0000, v170
	v_lshlrev_b32_e32 v202, 16, v171
	v_and_b32_e32 v203, 0xffff0000, v171
	v_lshlrev_b32_e32 v182, 16, v172
	v_and_b32_e32 v183, 0xffff0000, v172
	v_lshlrev_b32_e32 v184, 16, v173
	v_and_b32_e32 v185, 0xffff0000, v173
	v_mul_f32_e32 v200, v190, v200
	v_mul_f32_e32 v201, v191, v201
	v_mul_f32_e32 v202, v192, v202
	v_mul_f32_e32 v203, v193, v203
	v_mul_f32_e32 v182, v194, v182
	v_mul_f32_e32 v183, v195, v183
	v_mul_f32_e32 v184, v196, v184
	v_mul_f32_e32 v185, v197, v185
	v_cvt_pk_bf16_f32 v190, v200, v201
	v_cvt_pk_bf16_f32 v191, v202, v203
	v_cvt_pk_bf16_f32 v192, v182, v183
	v_cvt_pk_bf16_f32 v193, v184, v185
	s_mov_b64 s[10:11], 0x40000
	v_lshl_add_u64 v[242:243], v[168:169], 0, s[10:11]
	global_store_dwordx4 v[242:243], v[190:193], off offset:1792
	s_nop 1
	s_waitcnt vmcnt(9)
	v_add_f32_e32 v190, v38, v160
	v_add_f32_e32 v191, v39, v161
	v_add_f32_e32 v192, v40, v162
	v_add_f32_e32 v193, v41, v163
	v_add_f32_e32 v194, v34, v164
	v_add_f32_e32 v195, v35, v165
	v_add_f32_e32 v196, v36, v166
	v_add_f32_e32 v197, v37, v167
	v_mul_f32_e32 v190, 0xbfb8aa3b, v190
	v_mul_f32_e32 v191, 0xbfb8aa3b, v191
	v_mul_f32_e32 v192, 0xbfb8aa3b, v192
	v_mul_f32_e32 v193, 0xbfb8aa3b, v193
	v_mul_f32_e32 v194, 0xbfb8aa3b, v194
	v_mul_f32_e32 v195, 0xbfb8aa3b, v195
	v_mul_f32_e32 v196, 0xbfb8aa3b, v196
	v_mul_f32_e32 v197, 0xbfb8aa3b, v197
	v_exp_f32_e32 v190, v190
	v_exp_f32_e32 v191, v191
	v_exp_f32_e32 v192, v192
	v_exp_f32_e32 v193, v193
	v_exp_f32_e32 v194, v194
	v_exp_f32_e32 v195, v195
	v_exp_f32_e32 v196, v196
	v_exp_f32_e32 v197, v197
	v_add_f32_e32 v190, 1.0, v190
	v_add_f32_e32 v191, 1.0, v191
	v_add_f32_e32 v192, 1.0, v192
	v_add_f32_e32 v193, 1.0, v193
	v_add_f32_e32 v194, 1.0, v194
	v_add_f32_e32 v195, 1.0, v195
	v_add_f32_e32 v196, 1.0, v196
	v_add_f32_e32 v197, 1.0, v197
	v_rcp_f32_e32 v190, v190
	v_rcp_f32_e32 v191, v191
	v_rcp_f32_e32 v192, v192
	v_rcp_f32_e32 v193, v193
	v_rcp_f32_e32 v194, v194
	v_rcp_f32_e32 v195, v195
	v_rcp_f32_e32 v196, v196
	v_rcp_f32_e32 v197, v197
	v_lshlrev_b32_e32 v200, 16, v174
	v_and_b32_e32 v201, 0xffff0000, v174
	v_lshlrev_b32_e32 v202, 16, v175
	v_and_b32_e32 v203, 0xffff0000, v175
	v_lshlrev_b32_e32 v182, 16, v176
	v_and_b32_e32 v183, 0xffff0000, v176
	v_lshlrev_b32_e32 v184, 16, v177
	v_and_b32_e32 v185, 0xffff0000, v177
	v_mul_f32_e32 v200, v190, v200
	v_mul_f32_e32 v201, v191, v201
	v_mul_f32_e32 v202, v192, v202
	v_mul_f32_e32 v203, v193, v203
	v_mul_f32_e32 v182, v194, v182
	v_mul_f32_e32 v183, v195, v183
	v_mul_f32_e32 v184, v196, v184
	v_mul_f32_e32 v185, v197, v185
	v_cvt_pk_bf16_f32 v190, v200, v201
	v_cvt_pk_bf16_f32 v191, v202, v203
	v_cvt_pk_bf16_f32 v192, v182, v183
	v_cvt_pk_bf16_f32 v193, v184, v185
	s_mov_b64 s[10:11], 0x48000
	v_lshl_add_u64 v[198:199], v[168:169], 0, s[10:11]
	global_store_dwordx4 v[198:199], v[190:193], off offset:1792
	s_nop 1
	s_waitcnt vmcnt(8)
	v_add_f32_e32 v190, v22, v160
	v_add_f32_e32 v191, v23, v161
	v_add_f32_e32 v192, v24, v162
	v_add_f32_e32 v193, v25, v163
	v_add_f32_e32 v194, v18, v164
	v_add_f32_e32 v195, v19, v165
	v_add_f32_e32 v196, v20, v166
	v_add_f32_e32 v197, v21, v167
	v_mul_f32_e32 v190, 0xbfb8aa3b, v190
	v_mul_f32_e32 v191, 0xbfb8aa3b, v191
	v_mul_f32_e32 v192, 0xbfb8aa3b, v192
	v_mul_f32_e32 v193, 0xbfb8aa3b, v193
	v_mul_f32_e32 v194, 0xbfb8aa3b, v194
	v_mul_f32_e32 v195, 0xbfb8aa3b, v195
	v_mul_f32_e32 v196, 0xbfb8aa3b, v196
	v_mul_f32_e32 v197, 0xbfb8aa3b, v197
	v_exp_f32_e32 v190, v190
	v_exp_f32_e32 v191, v191
	v_exp_f32_e32 v192, v192
	v_exp_f32_e32 v193, v193
	v_exp_f32_e32 v194, v194
	v_exp_f32_e32 v195, v195
	v_exp_f32_e32 v196, v196
	v_exp_f32_e32 v197, v197
	v_add_f32_e32 v190, 1.0, v190
	v_add_f32_e32 v191, 1.0, v191
	v_add_f32_e32 v192, 1.0, v192
	v_add_f32_e32 v193, 1.0, v193
	v_add_f32_e32 v194, 1.0, v194
	v_add_f32_e32 v195, 1.0, v195
	v_add_f32_e32 v196, 1.0, v196
	v_add_f32_e32 v197, 1.0, v197
	v_rcp_f32_e32 v190, v190
	v_rcp_f32_e32 v191, v191
	v_rcp_f32_e32 v192, v192
	v_rcp_f32_e32 v193, v193
	v_rcp_f32_e32 v194, v194
	v_rcp_f32_e32 v195, v195
	v_rcp_f32_e32 v196, v196
	v_rcp_f32_e32 v197, v197
	v_lshlrev_b32_e32 v200, 16, v178
	v_and_b32_e32 v201, 0xffff0000, v178
	v_lshlrev_b32_e32 v202, 16, v179
	v_and_b32_e32 v203, 0xffff0000, v179
	v_lshlrev_b32_e32 v182, 16, v180
	v_and_b32_e32 v183, 0xffff0000, v180
	v_lshlrev_b32_e32 v184, 16, v181
	v_and_b32_e32 v185, 0xffff0000, v181
	v_mul_f32_e32 v200, v190, v200
	v_mul_f32_e32 v201, v191, v201
	v_mul_f32_e32 v202, v192, v202
	v_mul_f32_e32 v203, v193, v203
	v_mul_f32_e32 v182, v194, v182
	v_mul_f32_e32 v183, v195, v183
	v_mul_f32_e32 v184, v196, v184
	v_mul_f32_e32 v185, v197, v185
	v_cvt_pk_bf16_f32 v190, v200, v201
	v_cvt_pk_bf16_f32 v191, v202, v203
	v_cvt_pk_bf16_f32 v192, v182, v183
	v_cvt_pk_bf16_f32 v193, v184, v185
	s_mov_b64 s[10:11], 0x50000
	v_lshl_add_u64 v[242:243], v[168:169], 0, s[10:11]
	global_store_dwordx4 v[242:243], v[190:193], off offset:1792
	s_nop 1
	s_waitcnt vmcnt(7)
	v_add_f32_e32 v190, v6, v160
	v_add_f32_e32 v191, v7, v161
	v_add_f32_e32 v192, v8, v162
	v_add_f32_e32 v193, v9, v163
	v_add_f32_e32 v194, v2, v164
	v_add_f32_e32 v195, v3, v165
	v_add_f32_e32 v196, v4, v166
	v_add_f32_e32 v197, v5, v167
	v_mul_f32_e32 v190, 0xbfb8aa3b, v190
	v_mul_f32_e32 v191, 0xbfb8aa3b, v191
	v_mul_f32_e32 v192, 0xbfb8aa3b, v192
	v_mul_f32_e32 v193, 0xbfb8aa3b, v193
	v_mul_f32_e32 v194, 0xbfb8aa3b, v194
	v_mul_f32_e32 v195, 0xbfb8aa3b, v195
	v_mul_f32_e32 v196, 0xbfb8aa3b, v196
	v_mul_f32_e32 v197, 0xbfb8aa3b, v197
	v_exp_f32_e32 v190, v190
	v_exp_f32_e32 v191, v191
	v_exp_f32_e32 v192, v192
	v_exp_f32_e32 v193, v193
	v_exp_f32_e32 v194, v194
	v_exp_f32_e32 v195, v195
	v_exp_f32_e32 v196, v196
	v_exp_f32_e32 v197, v197
	v_add_f32_e32 v190, 1.0, v190
	v_add_f32_e32 v191, 1.0, v191
	v_add_f32_e32 v192, 1.0, v192
	v_add_f32_e32 v193, 1.0, v193
	v_add_f32_e32 v194, 1.0, v194
	v_add_f32_e32 v195, 1.0, v195
	v_add_f32_e32 v196, 1.0, v196
	v_add_f32_e32 v197, 1.0, v197
	v_rcp_f32_e32 v190, v190
	v_rcp_f32_e32 v191, v191
	v_rcp_f32_e32 v192, v192
	v_rcp_f32_e32 v193, v193
	v_rcp_f32_e32 v194, v194
	v_rcp_f32_e32 v195, v195
	v_rcp_f32_e32 v196, v196
	v_rcp_f32_e32 v197, v197
	v_lshlrev_b32_e32 v200, 16, v186
	v_and_b32_e32 v201, 0xffff0000, v186
	v_lshlrev_b32_e32 v202, 16, v187
	v_and_b32_e32 v203, 0xffff0000, v187
	v_lshlrev_b32_e32 v182, 16, v188
	v_and_b32_e32 v183, 0xffff0000, v188
	v_lshlrev_b32_e32 v184, 16, v189
	v_and_b32_e32 v185, 0xffff0000, v189
	v_mul_f32_e32 v200, v190, v200
	v_mul_f32_e32 v201, v191, v201
	v_mul_f32_e32 v202, v192, v202
	v_mul_f32_e32 v203, v193, v203
	v_mul_f32_e32 v182, v194, v182
	v_mul_f32_e32 v183, v195, v183
	v_mul_f32_e32 v184, v196, v184
	v_mul_f32_e32 v185, v197, v185
	v_cvt_pk_bf16_f32 v190, v200, v201
	v_cvt_pk_bf16_f32 v191, v202, v203
	v_cvt_pk_bf16_f32 v192, v182, v183
	v_cvt_pk_bf16_f32 v193, v184, v185
	s_mov_b64 s[10:11], 0x58000
	v_lshl_add_u64 v[198:199], v[168:169], 0, s[10:11]
	global_store_dwordx4 v[198:199], v[190:193], off offset:1792
	s_nop 1
